# residual epilogue: cross-row sums of squares via v_permlane16/32_swap instead of two ds_bpermute round trips per row (f32, same association)
# speedup vs baseline: 1.0076x; 1.0076x over previous
.LBB0_493:
	s_lshl_b32 s17, s17, 8
	v_lshl_or_b32 v208, s16, 8, v236
	v_add_u32_e32 v120, s17, v233
	v_ashrrev_i32_e32 v209, 31, v208
	v_lshlrev_b64 v[224:225], 1, v[208:209]
	v_ashrrev_i32_e32 v121, 31, v120
	v_lshl_add_u64 v[122:123], s[20:21], 0, v[224:225]
	v_lshlrev_b64 v[226:227], 11, v[120:121]
	v_lshl_add_u64 v[124:125], v[122:123], 0, v[226:227]
	global_load_dwordx4 v[250:253], v[124:125], off
	global_load_dwordx4 v[184:187], v[124:125], off offset:256
	v_or_b32_e32 v124, 16, v120
	v_ashrrev_i32_e32 v125, 31, v124
	v_lshlrev_b64 v[222:223], 11, v[124:125]
	v_lshl_add_u64 v[124:125], v[122:123], 0, v[222:223]
	global_load_dwordx4 v[180:183], v[124:125], off
	global_load_dwordx4 v[176:179], v[124:125], off offset:256
	v_or_b32_e32 v124, 32, v120
	v_or_b32_e32 v120, 48, v120
	v_ashrrev_i32_e32 v125, 31, v124
	v_ashrrev_i32_e32 v121, 31, v120
	v_lshlrev_b64 v[220:221], 11, v[124:125]
	v_lshlrev_b64 v[218:219], 11, v[120:121]
	s_mov_b64 s[2:3], 0x40000
	v_lshl_add_u64 v[124:125], v[122:123], 0, v[220:221]
	v_lshl_add_u64 v[120:121], v[122:123], 0, v[218:219]
	v_lshl_add_u64 v[216:217], v[226:227], 0, s[2:3]
	s_mov_b64 s[30:31], 0x48000
	global_load_dwordx4 v[172:175], v[124:125], off
	global_load_dwordx4 v[160:163], v[124:125], off offset:256
	global_load_dwordx4 v[156:159], v[120:121], off
	global_load_dwordx4 v[152:155], v[120:121], off offset:256
	v_lshl_add_u64 v[120:121], v[122:123], 0, v[216:217]
	v_lshl_add_u64 v[214:215], v[226:227], 0, s[30:31]
	s_mov_b64 s[30:31], 0x50000
	global_load_dwordx4 v[148:151], v[120:121], off
	global_load_dwordx4 v[140:143], v[120:121], off offset:256
	v_lshl_add_u64 v[120:121], v[122:123], 0, v[214:215]
	v_lshl_add_u64 v[212:213], v[226:227], 0, s[30:31]
	s_mov_b64 s[30:31], 0x58000
	global_load_dwordx4 v[144:147], v[120:121], off
	global_load_dwordx4 v[136:139], v[120:121], off offset:256
	v_lshl_add_u64 v[120:121], v[122:123], 0, v[212:213]
	v_lshl_add_u64 v[210:211], v[226:227], 0, s[30:31]
	global_load_dwordx4 v[132:135], v[120:121], off
	global_load_dwordx4 v[128:131], v[120:121], off offset:256
	v_lshl_add_u64 v[120:121], v[122:123], 0, v[210:211]
	global_load_dwordx4 v[124:127], v[120:121], off
	s_nop 0
	global_load_dwordx4 v[120:123], v[120:121], off offset:256
	s_waitcnt vmcnt(0) lgkmcnt(0)
	v_lshlrev_b32_e32 v254, 16, v250
	v_fmac_f32_e32 v254, v235, v168
	v_and_b32_e32 v168, 0xffff0000, v250
	v_fmac_f32_e32 v168, v235, v169
	v_lshlrev_b32_e32 v169, 16, v251
	v_fmac_f32_e32 v169, v235, v170
	v_and_b32_e32 v170, 0xffff0000, v251
	v_fmac_f32_e32 v170, v235, v171
	v_cvt_pk_bf16_f32 v168, v254, v168
	v_cvt_pk_bf16_f32 v169, v169, v170
	v_lshlrev_b32_e32 v170, 16, v252
	v_fmac_f32_e32 v170, v235, v164
	v_and_b32_e32 v164, 0xffff0000, v252
	v_fmac_f32_e32 v164, v235, v165
	v_cvt_pk_bf16_f32 v170, v170, v164
	v_lshlrev_b32_e32 v164, 16, v253
	v_and_b32_e32 v165, 0xffff0000, v253
	v_fmac_f32_e32 v164, v235, v166
	v_fmac_f32_e32 v165, v235, v167
	v_cvt_pk_bf16_f32 v171, v164, v165
	v_lshl_add_u64 v[164:165], s[20:21], 0, v[226:227]
	v_lshl_add_u64 v[164:165], v[164:165], 0, v[224:225]
	v_and_b32_e32 v167, 0xffff0000, v168
	global_store_dwordx4 v[164:165], v[168:171], off
	v_lshlrev_b32_e32 v166, 16, v168
	v_mul_f32_e32 v167, v167, v167
	v_and_b32_e32 v168, 0xffff0000, v169
	v_fmac_f32_e32 v167, v166, v166
	v_lshlrev_b32_e32 v166, 16, v169
	v_mul_f32_e32 v168, v168, v168
	v_fmac_f32_e32 v168, v166, v166
	v_add_f32_e32 v166, v167, v168
	v_and_b32_e32 v168, 0xffff0000, v170
	v_lshlrev_b32_e32 v167, 16, v170
	v_mul_f32_e32 v168, v168, v168
	v_fmac_f32_e32 v168, v167, v167
	v_add_f32_e32 v166, v166, v168
	v_and_b32_e32 v168, 0xffff0000, v171
	v_lshlrev_b32_e32 v167, 16, v171
	v_mul_f32_e32 v168, v168, v168
	v_fmac_f32_e32 v168, v167, v167
	v_lshlrev_b32_e32 v167, 16, v184
	v_fmac_f32_e32 v167, v235, v116
	v_and_b32_e32 v116, 0xffff0000, v184
	v_fmac_f32_e32 v116, v235, v117
	v_lshlrev_b32_e32 v117, 16, v185
	v_fmac_f32_e32 v117, v235, v118
	v_and_b32_e32 v118, 0xffff0000, v185
	v_fmac_f32_e32 v118, v235, v119
	v_cvt_pk_bf16_f32 v116, v167, v116
	v_cvt_pk_bf16_f32 v117, v117, v118
	v_lshlrev_b32_e32 v118, 16, v186
	v_fmac_f32_e32 v118, v235, v112
	v_and_b32_e32 v112, 0xffff0000, v186
	v_fmac_f32_e32 v112, v235, v113
	v_and_b32_e32 v113, 0xffff0000, v187
	v_cvt_pk_bf16_f32 v118, v118, v112
	v_lshlrev_b32_e32 v112, 16, v187
	v_fmac_f32_e32 v113, v235, v115
	v_fmac_f32_e32 v112, v235, v114
	v_cvt_pk_bf16_f32 v119, v112, v113
	v_and_b32_e32 v113, 0xffff0000, v116
	v_lshlrev_b32_e32 v112, 16, v116
	v_mul_f32_e32 v113, v113, v113
	v_and_b32_e32 v114, 0xffff0000, v117
	v_fmac_f32_e32 v113, v112, v112
	v_lshlrev_b32_e32 v112, 16, v117
	v_mul_f32_e32 v114, v114, v114
	v_fmac_f32_e32 v114, v112, v112
	v_add_f32_e32 v112, v113, v114
	v_and_b32_e32 v114, 0xffff0000, v118
	v_lshlrev_b32_e32 v113, 16, v118
	v_mul_f32_e32 v114, v114, v114
	v_fmac_f32_e32 v114, v113, v113
	v_add_f32_e32 v112, v112, v114
	v_and_b32_e32 v114, 0xffff0000, v119
	v_lshlrev_b32_e32 v113, 16, v119
	v_mul_f32_e32 v114, v114, v114
	v_fmac_f32_e32 v114, v113, v113
	v_add_f32_e32 v166, v166, v168
	v_add_f32_e32 v112, v112, v114
	v_add_f32_e32 v112, v166, v112
	v_mov_b32_e32 v113, v112
	global_store_dwordx4 v[164:165], v[116:119], off offset:256
	s_nop 1
	v_permlane16_swap_b32_e32 v112, v113
	v_add_f32_e32 v112, v112, v113
	v_mov_b32_e32 v113, v112
	s_nop 1
	v_permlane32_swap_b32_e32 v112, v113
	s_and_saveexec_b64 s[30:31], s[4:5]
	s_cbranch_execz .LBB0_495
	v_add_f32_e32 v112, v112, v113
	ds_write_b32 v240, v112
.LBB0_495:
	s_or_b64 exec, exec, s[30:31]
	v_lshlrev_b32_e32 v112, 16, v180
	v_fmac_f32_e32 v112, v235, v108
	v_and_b32_e32 v108, 0xffff0000, v180
	v_fmac_f32_e32 v108, v235, v109
	v_lshlrev_b32_e32 v109, 16, v181
	v_fmac_f32_e32 v109, v235, v110
	v_and_b32_e32 v110, 0xffff0000, v181
	v_fmac_f32_e32 v110, v235, v111
	v_cvt_pk_bf16_f32 v108, v112, v108
	v_cvt_pk_bf16_f32 v109, v109, v110
	v_lshlrev_b32_e32 v110, 16, v182
	v_fmac_f32_e32 v110, v235, v104
	v_and_b32_e32 v104, 0xffff0000, v182
	v_fmac_f32_e32 v104, v235, v105
	v_cvt_pk_bf16_f32 v110, v110, v104
	v_lshlrev_b32_e32 v104, 16, v183
	v_and_b32_e32 v105, 0xffff0000, v183
	v_fmac_f32_e32 v104, v235, v106
	v_fmac_f32_e32 v105, v235, v107
	v_cvt_pk_bf16_f32 v111, v104, v105
	v_lshl_add_u64 v[104:105], s[20:21], 0, v[222:223]
	v_lshl_add_u64 v[104:105], v[208:209], 1, v[104:105]
	v_and_b32_e32 v107, 0xffff0000, v108
	global_store_dwordx4 v[104:105], v[108:111], off
	v_lshlrev_b32_e32 v106, 16, v108
	v_mul_f32_e32 v107, v107, v107
	v_and_b32_e32 v108, 0xffff0000, v109
	v_fmac_f32_e32 v107, v106, v106
	v_lshlrev_b32_e32 v106, 16, v109
	v_mul_f32_e32 v108, v108, v108
	v_fmac_f32_e32 v108, v106, v106
	v_add_f32_e32 v106, v107, v108
	v_and_b32_e32 v108, 0xffff0000, v110
	v_lshlrev_b32_e32 v107, 16, v110
	v_mul_f32_e32 v108, v108, v108
	v_fmac_f32_e32 v108, v107, v107
	v_add_f32_e32 v106, v106, v108
	v_and_b32_e32 v108, 0xffff0000, v111
	v_lshlrev_b32_e32 v107, 16, v111
	v_mul_f32_e32 v108, v108, v108
	v_fmac_f32_e32 v108, v107, v107
	v_lshlrev_b32_e32 v107, 16, v176
	v_fmac_f32_e32 v107, v235, v100
	v_and_b32_e32 v100, 0xffff0000, v176
	v_fmac_f32_e32 v100, v235, v101
	v_lshlrev_b32_e32 v101, 16, v177
	v_fmac_f32_e32 v101, v235, v102
	v_and_b32_e32 v102, 0xffff0000, v177
	v_fmac_f32_e32 v102, v235, v103
	v_cvt_pk_bf16_f32 v100, v107, v100
	v_cvt_pk_bf16_f32 v101, v101, v102
	v_lshlrev_b32_e32 v102, 16, v178
	v_fmac_f32_e32 v102, v235, v96
	v_and_b32_e32 v96, 0xffff0000, v178
	v_fmac_f32_e32 v96, v235, v97
	v_and_b32_e32 v97, 0xffff0000, v179
	v_cvt_pk_bf16_f32 v102, v102, v96
	v_lshlrev_b32_e32 v96, 16, v179
	v_fmac_f32_e32 v97, v235, v99
	v_fmac_f32_e32 v96, v235, v98
	v_cvt_pk_bf16_f32 v103, v96, v97
	v_and_b32_e32 v97, 0xffff0000, v100
	v_lshlrev_b32_e32 v96, 16, v100
	v_mul_f32_e32 v97, v97, v97
	v_and_b32_e32 v98, 0xffff0000, v101
	v_fmac_f32_e32 v97, v96, v96
	v_lshlrev_b32_e32 v96, 16, v101
	v_mul_f32_e32 v98, v98, v98
	v_fmac_f32_e32 v98, v96, v96
	v_add_f32_e32 v96, v97, v98
	v_and_b32_e32 v98, 0xffff0000, v102
	v_lshlrev_b32_e32 v97, 16, v102
	v_mul_f32_e32 v98, v98, v98
	v_fmac_f32_e32 v98, v97, v97
	v_add_f32_e32 v96, v96, v98
	v_and_b32_e32 v98, 0xffff0000, v103
	v_lshlrev_b32_e32 v97, 16, v103
	v_mul_f32_e32 v98, v98, v98
	v_fmac_f32_e32 v98, v97, v97
	v_add_f32_e32 v106, v106, v108
	v_add_f32_e32 v96, v96, v98
	v_add_f32_e32 v96, v106, v96
	v_mov_b32_e32 v97, v96
	global_store_dwordx4 v[104:105], v[100:103], off offset:256
	s_nop 1
	v_permlane16_swap_b32_e32 v96, v97
	v_add_f32_e32 v96, v96, v97
	v_mov_b32_e32 v97, v96
	s_nop 1
	v_permlane32_swap_b32_e32 v96, v97
	s_and_saveexec_b64 s[30:31], s[4:5]
	s_cbranch_execz .LBB0_497
	v_add_f32_e32 v96, v96, v97
	ds_write_b32 v241, v96
.LBB0_497:
	s_or_b64 exec, exec, s[30:31]
	v_lshlrev_b32_e32 v96, 16, v172
	v_fmac_f32_e32 v96, v235, v92
	v_and_b32_e32 v92, 0xffff0000, v172
	v_fmac_f32_e32 v92, v235, v93
	v_lshlrev_b32_e32 v93, 16, v173
	v_fmac_f32_e32 v93, v235, v94
	v_and_b32_e32 v94, 0xffff0000, v173
	v_fmac_f32_e32 v94, v235, v95
	v_cvt_pk_bf16_f32 v92, v96, v92
	v_cvt_pk_bf16_f32 v93, v93, v94
	v_lshlrev_b32_e32 v94, 16, v174
	v_fmac_f32_e32 v94, v235, v88
	v_and_b32_e32 v88, 0xffff0000, v174
	v_fmac_f32_e32 v88, v235, v89
	v_cvt_pk_bf16_f32 v94, v94, v88
	v_lshlrev_b32_e32 v88, 16, v175
	v_and_b32_e32 v89, 0xffff0000, v175
	v_fmac_f32_e32 v88, v235, v90
	v_fmac_f32_e32 v89, v235, v91
	v_cvt_pk_bf16_f32 v95, v88, v89
	v_lshl_add_u64 v[88:89], s[20:21], 0, v[220:221]
	v_lshl_add_u64 v[88:89], v[208:209], 1, v[88:89]
	v_and_b32_e32 v91, 0xffff0000, v92
	global_store_dwordx4 v[88:89], v[92:95], off
	v_lshlrev_b32_e32 v90, 16, v92
	v_mul_f32_e32 v91, v91, v91
	v_and_b32_e32 v92, 0xffff0000, v93
	v_fmac_f32_e32 v91, v90, v90
	v_lshlrev_b32_e32 v90, 16, v93
	v_mul_f32_e32 v92, v92, v92
	v_fmac_f32_e32 v92, v90, v90
	v_add_f32_e32 v90, v91, v92
	v_and_b32_e32 v92, 0xffff0000, v94
	v_lshlrev_b32_e32 v91, 16, v94
	v_mul_f32_e32 v92, v92, v92
	v_fmac_f32_e32 v92, v91, v91
	v_add_f32_e32 v90, v90, v92
	v_and_b32_e32 v92, 0xffff0000, v95
	v_lshlrev_b32_e32 v91, 16, v95
	v_mul_f32_e32 v92, v92, v92
	v_fmac_f32_e32 v92, v91, v91
	v_lshlrev_b32_e32 v91, 16, v160
	v_fmac_f32_e32 v91, v235, v84
	v_and_b32_e32 v84, 0xffff0000, v160
	v_fmac_f32_e32 v84, v235, v85
	v_lshlrev_b32_e32 v85, 16, v161
	v_fmac_f32_e32 v85, v235, v86
	v_and_b32_e32 v86, 0xffff0000, v161
	v_fmac_f32_e32 v86, v235, v87
	v_cvt_pk_bf16_f32 v84, v91, v84
	v_cvt_pk_bf16_f32 v85, v85, v86
	v_lshlrev_b32_e32 v86, 16, v162
	v_fmac_f32_e32 v86, v235, v80
	v_and_b32_e32 v80, 0xffff0000, v162
	v_fmac_f32_e32 v80, v235, v81
	v_and_b32_e32 v81, 0xffff0000, v163
	v_cvt_pk_bf16_f32 v86, v86, v80
	v_lshlrev_b32_e32 v80, 16, v163
	v_fmac_f32_e32 v81, v235, v83
	v_fmac_f32_e32 v80, v235, v82
	v_cvt_pk_bf16_f32 v87, v80, v81
	v_and_b32_e32 v81, 0xffff0000, v84
	v_lshlrev_b32_e32 v80, 16, v84
	v_mul_f32_e32 v81, v81, v81
	v_and_b32_e32 v82, 0xffff0000, v85
	v_fmac_f32_e32 v81, v80, v80
	v_lshlrev_b32_e32 v80, 16, v85
	v_mul_f32_e32 v82, v82, v82
	v_fmac_f32_e32 v82, v80, v80
	v_add_f32_e32 v80, v81, v82
	v_and_b32_e32 v82, 0xffff0000, v86
	v_lshlrev_b32_e32 v81, 16, v86
	v_mul_f32_e32 v82, v82, v82
	v_fmac_f32_e32 v82, v81, v81
	v_add_f32_e32 v80, v80, v82
	v_and_b32_e32 v82, 0xffff0000, v87
	v_lshlrev_b32_e32 v81, 16, v87
	v_mul_f32_e32 v82, v82, v82
	v_fmac_f32_e32 v82, v81, v81
	v_add_f32_e32 v90, v90, v92
	v_add_f32_e32 v80, v80, v82
	v_add_f32_e32 v80, v90, v80
	v_mov_b32_e32 v81, v80
	global_store_dwordx4 v[88:89], v[84:87], off offset:256
	s_nop 1
	v_permlane16_swap_b32_e32 v80, v81
	v_add_f32_e32 v80, v80, v81
	v_mov_b32_e32 v81, v80
	s_nop 1
	v_permlane32_swap_b32_e32 v80, v81
	s_and_saveexec_b64 s[30:31], s[4:5]
	s_cbranch_execz .LBB0_499
	v_add_f32_e32 v80, v80, v81
	ds_write_b32 v242, v80
.LBB0_499:
	s_or_b64 exec, exec, s[30:31]
	v_lshlrev_b32_e32 v80, 16, v156
	v_fmac_f32_e32 v80, v235, v76
	v_and_b32_e32 v76, 0xffff0000, v156
	v_fmac_f32_e32 v76, v235, v77
	v_lshlrev_b32_e32 v77, 16, v157
	v_fmac_f32_e32 v77, v235, v78
	v_and_b32_e32 v78, 0xffff0000, v157
	v_fmac_f32_e32 v78, v235, v79
	v_cvt_pk_bf16_f32 v76, v80, v76
	v_cvt_pk_bf16_f32 v77, v77, v78
	v_lshlrev_b32_e32 v78, 16, v158
	v_fmac_f32_e32 v78, v235, v72
	v_and_b32_e32 v72, 0xffff0000, v158
	v_fmac_f32_e32 v72, v235, v73
	v_cvt_pk_bf16_f32 v78, v78, v72
	v_lshlrev_b32_e32 v72, 16, v159
	v_and_b32_e32 v73, 0xffff0000, v159
	v_fmac_f32_e32 v72, v235, v74
	v_fmac_f32_e32 v73, v235, v75
	v_cvt_pk_bf16_f32 v79, v72, v73
	v_lshl_add_u64 v[72:73], s[20:21], 0, v[218:219]
	v_lshl_add_u64 v[72:73], v[208:209], 1, v[72:73]
	v_and_b32_e32 v75, 0xffff0000, v76
	global_store_dwordx4 v[72:73], v[76:79], off
	v_lshlrev_b32_e32 v74, 16, v76
	v_mul_f32_e32 v75, v75, v75
	v_and_b32_e32 v76, 0xffff0000, v77
	v_fmac_f32_e32 v75, v74, v74
	v_lshlrev_b32_e32 v74, 16, v77
	v_mul_f32_e32 v76, v76, v76
	v_fmac_f32_e32 v76, v74, v74
	v_add_f32_e32 v74, v75, v76
	v_and_b32_e32 v76, 0xffff0000, v78
	v_lshlrev_b32_e32 v75, 16, v78
	v_mul_f32_e32 v76, v76, v76
	v_fmac_f32_e32 v76, v75, v75
	v_add_f32_e32 v74, v74, v76
	v_and_b32_e32 v76, 0xffff0000, v79
	v_lshlrev_b32_e32 v75, 16, v79
	v_mul_f32_e32 v76, v76, v76
	v_fmac_f32_e32 v76, v75, v75
	v_lshlrev_b32_e32 v75, 16, v152
	v_fmac_f32_e32 v75, v235, v68
	v_and_b32_e32 v68, 0xffff0000, v152
	v_fmac_f32_e32 v68, v235, v69
	v_lshlrev_b32_e32 v69, 16, v153
	v_fmac_f32_e32 v69, v235, v70
	v_and_b32_e32 v70, 0xffff0000, v153
	v_fmac_f32_e32 v70, v235, v71
	v_cvt_pk_bf16_f32 v68, v75, v68
	v_cvt_pk_bf16_f32 v69, v69, v70
	v_lshlrev_b32_e32 v70, 16, v154
	v_fmac_f32_e32 v70, v235, v64
	v_and_b32_e32 v64, 0xffff0000, v154
	v_fmac_f32_e32 v64, v235, v65
	v_and_b32_e32 v65, 0xffff0000, v155
	v_cvt_pk_bf16_f32 v70, v70, v64
	v_lshlrev_b32_e32 v64, 16, v155
	v_fmac_f32_e32 v65, v235, v67
	v_fmac_f32_e32 v64, v235, v66
	v_cvt_pk_bf16_f32 v71, v64, v65
	v_and_b32_e32 v65, 0xffff0000, v68
	v_lshlrev_b32_e32 v64, 16, v68
	v_mul_f32_e32 v65, v65, v65
	v_and_b32_e32 v66, 0xffff0000, v69
	v_fmac_f32_e32 v65, v64, v64
	v_lshlrev_b32_e32 v64, 16, v69
	v_mul_f32_e32 v66, v66, v66
	v_fmac_f32_e32 v66, v64, v64
	v_add_f32_e32 v64, v65, v66
	v_and_b32_e32 v66, 0xffff0000, v70
	v_lshlrev_b32_e32 v65, 16, v70
	v_mul_f32_e32 v66, v66, v66
	v_fmac_f32_e32 v66, v65, v65
	v_add_f32_e32 v64, v64, v66
	v_and_b32_e32 v66, 0xffff0000, v71
	v_lshlrev_b32_e32 v65, 16, v71
	v_mul_f32_e32 v66, v66, v66
	v_fmac_f32_e32 v66, v65, v65
	v_add_f32_e32 v74, v74, v76
	v_add_f32_e32 v64, v64, v66
	v_add_f32_e32 v64, v74, v64
	v_mov_b32_e32 v65, v64
	global_store_dwordx4 v[72:73], v[68:71], off offset:256
	s_nop 1
	v_permlane16_swap_b32_e32 v64, v65
	v_add_f32_e32 v64, v64, v65
	v_mov_b32_e32 v65, v64
	s_nop 1
	v_permlane32_swap_b32_e32 v64, v65
	s_and_saveexec_b64 s[30:31], s[4:5]
	s_cbranch_execz .LBB0_501
	v_add_f32_e32 v64, v64, v65
	ds_write_b32 v243, v64
.LBB0_501:
	s_or_b64 exec, exec, s[30:31]
	v_lshlrev_b32_e32 v64, 16, v148
	v_fmac_f32_e32 v64, v235, v60
	v_and_b32_e32 v60, 0xffff0000, v148
	v_fmac_f32_e32 v60, v235, v61
	v_lshlrev_b32_e32 v61, 16, v149
	v_fmac_f32_e32 v61, v235, v62
	v_and_b32_e32 v62, 0xffff0000, v149
	v_fmac_f32_e32 v62, v235, v63
	v_cvt_pk_bf16_f32 v60, v64, v60
	v_cvt_pk_bf16_f32 v61, v61, v62
	v_lshlrev_b32_e32 v62, 16, v150
	v_fmac_f32_e32 v62, v235, v56
	v_and_b32_e32 v56, 0xffff0000, v150
	v_fmac_f32_e32 v56, v235, v57
	v_cvt_pk_bf16_f32 v62, v62, v56
	v_lshlrev_b32_e32 v56, 16, v151
	v_and_b32_e32 v57, 0xffff0000, v151
	v_fmac_f32_e32 v56, v235, v58
	v_fmac_f32_e32 v57, v235, v59
	v_cvt_pk_bf16_f32 v63, v56, v57
	v_lshl_add_u64 v[56:57], s[20:21], 0, v[216:217]
	v_lshl_add_u64 v[56:57], v[208:209], 1, v[56:57]
	v_and_b32_e32 v59, 0xffff0000, v60
	global_store_dwordx4 v[56:57], v[60:63], off
	v_lshlrev_b32_e32 v58, 16, v60
	v_mul_f32_e32 v59, v59, v59
	v_and_b32_e32 v60, 0xffff0000, v61
	v_fmac_f32_e32 v59, v58, v58
	v_lshlrev_b32_e32 v58, 16, v61
	v_mul_f32_e32 v60, v60, v60
	v_fmac_f32_e32 v60, v58, v58
	v_add_f32_e32 v58, v59, v60
	v_and_b32_e32 v60, 0xffff0000, v62
	v_lshlrev_b32_e32 v59, 16, v62
	v_mul_f32_e32 v60, v60, v60
	v_fmac_f32_e32 v60, v59, v59
	v_add_f32_e32 v58, v58, v60
	v_and_b32_e32 v60, 0xffff0000, v63
	v_lshlrev_b32_e32 v59, 16, v63
	v_mul_f32_e32 v60, v60, v60
	v_fmac_f32_e32 v60, v59, v59
	v_lshlrev_b32_e32 v59, 16, v140
	v_fmac_f32_e32 v59, v235, v52
	v_and_b32_e32 v52, 0xffff0000, v140
	v_fmac_f32_e32 v52, v235, v53
	v_lshlrev_b32_e32 v53, 16, v141
	v_fmac_f32_e32 v53, v235, v54
	v_and_b32_e32 v54, 0xffff0000, v141
	v_fmac_f32_e32 v54, v235, v55
	v_cvt_pk_bf16_f32 v52, v59, v52
	v_cvt_pk_bf16_f32 v53, v53, v54
	v_lshlrev_b32_e32 v54, 16, v142
	v_fmac_f32_e32 v54, v235, v48
	v_and_b32_e32 v48, 0xffff0000, v142
	v_fmac_f32_e32 v48, v235, v49
	v_and_b32_e32 v49, 0xffff0000, v143
	v_cvt_pk_bf16_f32 v54, v54, v48
	v_lshlrev_b32_e32 v48, 16, v143
	v_fmac_f32_e32 v49, v235, v51
	v_fmac_f32_e32 v48, v235, v50
	v_cvt_pk_bf16_f32 v55, v48, v49
	v_and_b32_e32 v49, 0xffff0000, v52
	v_lshlrev_b32_e32 v48, 16, v52
	v_mul_f32_e32 v49, v49, v49
	v_and_b32_e32 v50, 0xffff0000, v53
	v_fmac_f32_e32 v49, v48, v48
	v_lshlrev_b32_e32 v48, 16, v53
	v_mul_f32_e32 v50, v50, v50
	v_fmac_f32_e32 v50, v48, v48
	v_add_f32_e32 v48, v49, v50
	v_and_b32_e32 v50, 0xffff0000, v54
	v_lshlrev_b32_e32 v49, 16, v54
	v_mul_f32_e32 v50, v50, v50
	v_fmac_f32_e32 v50, v49, v49
	v_add_f32_e32 v48, v48, v50
	v_and_b32_e32 v50, 0xffff0000, v55
	v_lshlrev_b32_e32 v49, 16, v55
	v_mul_f32_e32 v50, v50, v50
	v_fmac_f32_e32 v50, v49, v49
	v_add_f32_e32 v58, v58, v60
	v_add_f32_e32 v48, v48, v50
	v_add_f32_e32 v48, v58, v48
	v_mov_b32_e32 v49, v48
	global_store_dwordx4 v[56:57], v[52:55], off offset:256
	s_nop 1
	v_permlane16_swap_b32_e32 v48, v49
	v_add_f32_e32 v48, v48, v49
	v_mov_b32_e32 v49, v48
	s_nop 1
	v_permlane32_swap_b32_e32 v48, v49
	s_and_saveexec_b64 s[30:31], s[4:5]
	s_cbranch_execz .LBB0_503
	v_add_f32_e32 v48, v48, v49
	ds_write_b32 v244, v48
.LBB0_503:
	s_or_b64 exec, exec, s[30:31]
	v_lshlrev_b32_e32 v48, 16, v144
	v_fmac_f32_e32 v48, v235, v44
	v_and_b32_e32 v44, 0xffff0000, v144
	v_fmac_f32_e32 v44, v235, v45
	v_lshlrev_b32_e32 v45, 16, v145
	v_fmac_f32_e32 v45, v235, v46
	v_and_b32_e32 v46, 0xffff0000, v145
	v_fmac_f32_e32 v46, v235, v47
	v_cvt_pk_bf16_f32 v44, v48, v44
	v_cvt_pk_bf16_f32 v45, v45, v46
	v_lshlrev_b32_e32 v46, 16, v146
	v_fmac_f32_e32 v46, v235, v40
	v_and_b32_e32 v40, 0xffff0000, v146
	v_fmac_f32_e32 v40, v235, v41
	v_cvt_pk_bf16_f32 v46, v46, v40
	v_lshlrev_b32_e32 v40, 16, v147
	v_and_b32_e32 v41, 0xffff0000, v147
	v_fmac_f32_e32 v40, v235, v42
	v_fmac_f32_e32 v41, v235, v43
	v_cvt_pk_bf16_f32 v47, v40, v41
	v_lshl_add_u64 v[40:41], s[20:21], 0, v[214:215]
	v_lshl_add_u64 v[40:41], v[208:209], 1, v[40:41]
	v_and_b32_e32 v43, 0xffff0000, v44
	global_store_dwordx4 v[40:41], v[44:47], off
	v_lshlrev_b32_e32 v42, 16, v44
	v_mul_f32_e32 v43, v43, v43
	v_and_b32_e32 v44, 0xffff0000, v45
	v_fmac_f32_e32 v43, v42, v42
	v_lshlrev_b32_e32 v42, 16, v45
	v_mul_f32_e32 v44, v44, v44
	v_fmac_f32_e32 v44, v42, v42
	v_add_f32_e32 v42, v43, v44
	v_and_b32_e32 v44, 0xffff0000, v46
	v_lshlrev_b32_e32 v43, 16, v46
	v_mul_f32_e32 v44, v44, v44
	v_fmac_f32_e32 v44, v43, v43
	v_add_f32_e32 v42, v42, v44
	v_and_b32_e32 v44, 0xffff0000, v47
	v_lshlrev_b32_e32 v43, 16, v47
	v_mul_f32_e32 v44, v44, v44
	v_fmac_f32_e32 v44, v43, v43
	v_lshlrev_b32_e32 v43, 16, v136
	v_fmac_f32_e32 v43, v235, v36
	v_and_b32_e32 v36, 0xffff0000, v136
	v_fmac_f32_e32 v36, v235, v37
	v_lshlrev_b32_e32 v37, 16, v137
	v_fmac_f32_e32 v37, v235, v38
	v_and_b32_e32 v38, 0xffff0000, v137
	v_fmac_f32_e32 v38, v235, v39
	v_cvt_pk_bf16_f32 v36, v43, v36
	v_cvt_pk_bf16_f32 v37, v37, v38
	v_lshlrev_b32_e32 v38, 16, v138
	v_fmac_f32_e32 v38, v235, v32
	v_and_b32_e32 v32, 0xffff0000, v138
	v_fmac_f32_e32 v32, v235, v33
	v_and_b32_e32 v33, 0xffff0000, v139
	v_cvt_pk_bf16_f32 v38, v38, v32
	v_lshlrev_b32_e32 v32, 16, v139
	v_fmac_f32_e32 v33, v235, v35
	v_fmac_f32_e32 v32, v235, v34
	v_cvt_pk_bf16_f32 v39, v32, v33
	v_and_b32_e32 v33, 0xffff0000, v36
	v_lshlrev_b32_e32 v32, 16, v36
	v_mul_f32_e32 v33, v33, v33
	v_and_b32_e32 v34, 0xffff0000, v37
	v_fmac_f32_e32 v33, v32, v32
	v_lshlrev_b32_e32 v32, 16, v37
	v_mul_f32_e32 v34, v34, v34
	v_fmac_f32_e32 v34, v32, v32
	v_add_f32_e32 v32, v33, v34
	v_and_b32_e32 v34, 0xffff0000, v38
	v_lshlrev_b32_e32 v33, 16, v38
	v_mul_f32_e32 v34, v34, v34
	v_fmac_f32_e32 v34, v33, v33
	v_add_f32_e32 v32, v32, v34
	v_and_b32_e32 v34, 0xffff0000, v39
	v_lshlrev_b32_e32 v33, 16, v39
	v_mul_f32_e32 v34, v34, v34
	v_fmac_f32_e32 v34, v33, v33
	v_add_f32_e32 v42, v42, v44
	v_add_f32_e32 v32, v32, v34
	v_add_f32_e32 v32, v42, v32
	v_mov_b32_e32 v33, v32
	global_store_dwordx4 v[40:41], v[36:39], off offset:256
	s_nop 1
	v_permlane16_swap_b32_e32 v32, v33
	v_add_f32_e32 v32, v32, v33
	v_mov_b32_e32 v33, v32
	s_nop 1
	v_permlane32_swap_b32_e32 v32, v33
	s_and_saveexec_b64 s[30:31], s[4:5]
	s_cbranch_execz .LBB0_505
	v_add_f32_e32 v32, v32, v33
	ds_write_b32 v245, v32
.LBB0_505:
	s_or_b64 exec, exec, s[30:31]
	v_lshlrev_b32_e32 v32, 16, v132
	v_fmac_f32_e32 v32, v235, v28
	v_and_b32_e32 v28, 0xffff0000, v132
	v_fmac_f32_e32 v28, v235, v29
	v_lshlrev_b32_e32 v29, 16, v133
	v_fmac_f32_e32 v29, v235, v30
	v_and_b32_e32 v30, 0xffff0000, v133
	v_fmac_f32_e32 v30, v235, v31
	v_cvt_pk_bf16_f32 v28, v32, v28
	v_cvt_pk_bf16_f32 v29, v29, v30
	v_lshlrev_b32_e32 v30, 16, v134
	v_fmac_f32_e32 v30, v235, v24
	v_and_b32_e32 v24, 0xffff0000, v134
	v_fmac_f32_e32 v24, v235, v25
	v_cvt_pk_bf16_f32 v30, v30, v24
	v_lshlrev_b32_e32 v24, 16, v135
	v_and_b32_e32 v25, 0xffff0000, v135
	v_fmac_f32_e32 v24, v235, v26
	v_fmac_f32_e32 v25, v235, v27
	v_cvt_pk_bf16_f32 v31, v24, v25
	v_lshl_add_u64 v[24:25], s[20:21], 0, v[212:213]
	v_lshl_add_u64 v[24:25], v[208:209], 1, v[24:25]
	v_and_b32_e32 v27, 0xffff0000, v28
	global_store_dwordx4 v[24:25], v[28:31], off
	v_lshlrev_b32_e32 v26, 16, v28
	v_mul_f32_e32 v27, v27, v27
	v_and_b32_e32 v28, 0xffff0000, v29
	v_fmac_f32_e32 v27, v26, v26
	v_lshlrev_b32_e32 v26, 16, v29
	v_mul_f32_e32 v28, v28, v28
	v_fmac_f32_e32 v28, v26, v26
	v_add_f32_e32 v26, v27, v28
	v_and_b32_e32 v28, 0xffff0000, v30
	v_lshlrev_b32_e32 v27, 16, v30
	v_mul_f32_e32 v28, v28, v28
	v_fmac_f32_e32 v28, v27, v27
	v_add_f32_e32 v26, v26, v28
	v_and_b32_e32 v28, 0xffff0000, v31
	v_lshlrev_b32_e32 v27, 16, v31
	v_mul_f32_e32 v28, v28, v28
	v_fmac_f32_e32 v28, v27, v27
	v_lshlrev_b32_e32 v27, 16, v128
	v_fmac_f32_e32 v27, v235, v20
	v_and_b32_e32 v20, 0xffff0000, v128
	v_fmac_f32_e32 v20, v235, v21
	v_lshlrev_b32_e32 v21, 16, v129
	v_fmac_f32_e32 v21, v235, v22
	v_and_b32_e32 v22, 0xffff0000, v129
	v_fmac_f32_e32 v22, v235, v23
	v_cvt_pk_bf16_f32 v20, v27, v20
	v_cvt_pk_bf16_f32 v21, v21, v22
	v_lshlrev_b32_e32 v22, 16, v130
	v_fmac_f32_e32 v22, v235, v16
	v_and_b32_e32 v16, 0xffff0000, v130
	v_fmac_f32_e32 v16, v235, v17
	v_and_b32_e32 v17, 0xffff0000, v131
	v_cvt_pk_bf16_f32 v22, v22, v16
	v_lshlrev_b32_e32 v16, 16, v131
	v_fmac_f32_e32 v17, v235, v19
	v_fmac_f32_e32 v16, v235, v18
	v_cvt_pk_bf16_f32 v23, v16, v17
	v_and_b32_e32 v17, 0xffff0000, v20
	v_lshlrev_b32_e32 v16, 16, v20
	v_mul_f32_e32 v17, v17, v17
	v_and_b32_e32 v18, 0xffff0000, v21
	v_fmac_f32_e32 v17, v16, v16
	v_lshlrev_b32_e32 v16, 16, v21
	v_mul_f32_e32 v18, v18, v18
	v_fmac_f32_e32 v18, v16, v16
	v_add_f32_e32 v16, v17, v18
	v_and_b32_e32 v18, 0xffff0000, v22
	v_lshlrev_b32_e32 v17, 16, v22
	v_mul_f32_e32 v18, v18, v18
	v_fmac_f32_e32 v18, v17, v17
	v_add_f32_e32 v16, v16, v18
	v_and_b32_e32 v18, 0xffff0000, v23
	v_lshlrev_b32_e32 v17, 16, v23
	v_mul_f32_e32 v18, v18, v18
	v_fmac_f32_e32 v18, v17, v17
	v_add_f32_e32 v26, v26, v28
	v_add_f32_e32 v16, v16, v18
	v_add_f32_e32 v16, v26, v16
	v_mov_b32_e32 v17, v16
	global_store_dwordx4 v[24:25], v[20:23], off offset:256
	s_nop 1
	v_permlane16_swap_b32_e32 v16, v17
	v_add_f32_e32 v16, v16, v17
	v_mov_b32_e32 v17, v16
	s_nop 1
	v_permlane32_swap_b32_e32 v16, v17
	s_and_saveexec_b64 s[30:31], s[4:5]
	s_cbranch_execz .LBB0_507
	v_add_f32_e32 v16, v16, v17
	ds_write_b32 v246, v16
.LBB0_507:
	s_or_b64 exec, exec, s[30:31]
	v_lshlrev_b32_e32 v16, 16, v124
	v_fmac_f32_e32 v16, v235, v12
	v_and_b32_e32 v12, 0xffff0000, v124
	v_fmac_f32_e32 v12, v235, v13
	v_lshlrev_b32_e32 v13, 16, v125
	v_fmac_f32_e32 v13, v235, v14
	v_and_b32_e32 v14, 0xffff0000, v125
	v_fmac_f32_e32 v14, v235, v15
	v_cvt_pk_bf16_f32 v12, v16, v12
	v_cvt_pk_bf16_f32 v13, v13, v14
	v_lshlrev_b32_e32 v14, 16, v126
	v_fmac_f32_e32 v14, v235, v8
	v_and_b32_e32 v8, 0xffff0000, v126
	v_fmac_f32_e32 v8, v235, v9
	v_cvt_pk_bf16_f32 v14, v14, v8
	v_lshlrev_b32_e32 v8, 16, v127
	v_and_b32_e32 v9, 0xffff0000, v127
	v_fmac_f32_e32 v8, v235, v10
	v_fmac_f32_e32 v9, v235, v11
	v_cvt_pk_bf16_f32 v15, v8, v9
	v_lshl_add_u64 v[8:9], s[20:21], 0, v[210:211]
	v_lshl_add_u64 v[8:9], v[208:209], 1, v[8:9]
	v_and_b32_e32 v11, 0xffff0000, v12
	global_store_dwordx4 v[8:9], v[12:15], off
	v_lshlrev_b32_e32 v10, 16, v12
	v_mul_f32_e32 v11, v11, v11
	v_and_b32_e32 v12, 0xffff0000, v13
	v_fmac_f32_e32 v11, v10, v10
	v_lshlrev_b32_e32 v10, 16, v13
	v_mul_f32_e32 v12, v12, v12
	v_fmac_f32_e32 v12, v10, v10
	v_add_f32_e32 v10, v11, v12
	v_and_b32_e32 v12, 0xffff0000, v14
	v_lshlrev_b32_e32 v11, 16, v14
	v_mul_f32_e32 v12, v12, v12
	v_fmac_f32_e32 v12, v11, v11
	v_add_f32_e32 v10, v10, v12
	v_and_b32_e32 v12, 0xffff0000, v15
	v_lshlrev_b32_e32 v11, 16, v15
	v_mul_f32_e32 v12, v12, v12
	v_fmac_f32_e32 v12, v11, v11
	v_lshlrev_b32_e32 v11, 16, v120
	v_fmac_f32_e32 v11, v235, v4
	v_and_b32_e32 v4, 0xffff0000, v120
	v_fmac_f32_e32 v4, v235, v5
	v_lshlrev_b32_e32 v5, 16, v121
	v_fmac_f32_e32 v5, v235, v6
	v_and_b32_e32 v6, 0xffff0000, v121
	v_fmac_f32_e32 v6, v235, v7
	v_cvt_pk_bf16_f32 v4, v11, v4
	v_cvt_pk_bf16_f32 v5, v5, v6
	v_lshlrev_b32_e32 v6, 16, v122
	v_fmac_f32_e32 v6, v235, v0
	v_and_b32_e32 v0, 0xffff0000, v122
	v_fmac_f32_e32 v0, v235, v1
	v_and_b32_e32 v1, 0xffff0000, v123
	v_cvt_pk_bf16_f32 v6, v6, v0
	v_lshlrev_b32_e32 v0, 16, v123
	v_fmac_f32_e32 v1, v235, v3
	v_fmac_f32_e32 v0, v235, v2
	v_cvt_pk_bf16_f32 v7, v0, v1
	v_and_b32_e32 v1, 0xffff0000, v4
	v_lshlrev_b32_e32 v0, 16, v4
	v_mul_f32_e32 v1, v1, v1
	v_and_b32_e32 v2, 0xffff0000, v5
	v_fmac_f32_e32 v1, v0, v0
	v_lshlrev_b32_e32 v0, 16, v5
	v_mul_f32_e32 v2, v2, v2
	v_fmac_f32_e32 v2, v0, v0
	v_add_f32_e32 v0, v1, v2
	v_and_b32_e32 v2, 0xffff0000, v6
	v_lshlrev_b32_e32 v1, 16, v6
	v_mul_f32_e32 v2, v2, v2
	v_fmac_f32_e32 v2, v1, v1
	v_add_f32_e32 v0, v0, v2
	v_and_b32_e32 v2, 0xffff0000, v7
	v_lshlrev_b32_e32 v1, 16, v7
	v_mul_f32_e32 v2, v2, v2
	v_fmac_f32_e32 v2, v1, v1
	v_add_f32_e32 v10, v10, v12
	v_add_f32_e32 v0, v0, v2
	v_add_f32_e32 v0, v10, v0
	v_mov_b32_e32 v1, v0
	global_store_dwordx4 v[8:9], v[4:7], off offset:256
	s_nop 1
	v_permlane16_swap_b32_e32 v0, v1
	v_add_f32_e32 v0, v0, v1
	v_mov_b32_e32 v1, v0
	s_nop 1
	v_permlane32_swap_b32_e32 v0, v1
	s_and_saveexec_b64 s[30:31], s[4:5]
	s_cbranch_execz .LBB0_509
	v_add_f32_e32 v0, v0, v1
	ds_write_b32 v247, v0
